# v48 + GEMM prologue: the trailing half's extra barrier moved after its K-tile 1 LDS-DMA loads (all 14 prologue loads of every wave issued before the first barrier)
# baseline (speedup 1.0000x reference)
.LBB0_120:
	v_and_b32_e32 v150, 15, v10
	v_and_b32_e32 v151, 63, v10
	v_bfe_u32 v152, v10, 4, 2
	v_and_b32_e32 v17, 48, v10
	v_lshlrev_b32_e32 v10, 2, v10
	s_and_b32 s5, s12, 3
	s_lshl_b32 s7, s11, 13
	v_lshl_or_b32 v17, v150, 6, v17
	v_and_b32_e32 v10, 32, v10
	s_add_i32 m0, s16, 0x18000
	v_lshl_add_u64 v[8:9], v[8:9], 0, s[88:89]
	s_lshl_b32 s56, s11, 6
	v_bitop3_b32 v18, v17, s7, v10 bitop3:0xde
	s_lshl_b32 s33, s5, 5
	s_lshl_b32 s7, s5, 12
	global_load_lds_dwordx4 v[8:9], off
	v_lshl_add_u64 v[6:7], v[6:7], 0, s[88:89]
	s_add_i32 m0, s16, 0x1a000
	s_add_i32 s52, s16, 0x8000
	s_add_i32 s90, s16, 0xa000
	global_load_lds_dwordx4 v[6:7], off
	v_lshl_add_u64 v[2:3], v[2:3], 0, s[88:89]
	s_mov_b32 m0, s52
	s_add_u32 s18, s8, 0x100080
	global_load_lds_dwordx4 v[2:3], off
	v_lshl_add_u64 v[2:3], v[4:5], 0, s[88:89]
	s_mov_b32 m0, s90
	s_addc_u32 s19, s9, 0
	global_load_lds_dwordx4 v[2:3], off
	s_add_i32 m0, s16, 0x1c000
	v_lshl_add_u64 v[2:3], s[18:19], 0, v[0:1]
	global_load_lds_dwordx4 v[2:3], off
	v_lshl_add_u64 v[2:3], s[18:19], 0, v[134:135]
	s_add_i32 m0, s16, 0x1e000
	v_bitop3_b32 v153, v17, s7, v10 bitop3:0xde
	global_load_lds_dwordx4 v[2:3], off
	s_cmp_lg_u32 s11, 1
	s_cbranch_scc1 .Lpro_skip0
	s_barrier
.Lpro_skip0:
	s_waitcnt vmcnt(8)
	s_barrier
	s_lshl_b32 s7, s12, 4
	v_lshlrev_b32_e32 v2, 16, v11
	s_and_b32 s18, s7, 0xffffffc0
	v_and_b32_e32 v2, 0xfffe0000, v2
	s_or_b32 s91, s5, 0xffffffb8
	s_ashr_i32 s19, s18, 31
	s_lshl_b32 s7, s12, 9
	v_lshl_add_u32 v2, v12, 13, v2
	v_and_b32_e32 v3, 1, v11
	s_cmpk_lt_u32 s10, 0x100
	v_lshl_or_b32 v2, v3, 6, v2
	s_cselect_b64 s[94:95], -1, 0
	s_lshl_b32 s12, s11, 11
	s_lshl_b32 s5, s5, 9
	s_lshl_b64 s[10:11], s[18:19], 2
	v_readlane_b32 s13, v254, 7
	v_lshl_add_u32 v136, v13, 1, v2
	v_lshlrev_b32_e32 v2, 16, v14
	s_add_u32 s54, s13, s10
	v_readlane_b32 s10, v254, 8
	v_and_b32_e32 v2, 0xfffe0000, v2
	s_waitcnt vmcnt(6)
	s_addc_u32 s60, s10, s11
	s_add_i32 s10, s12, 0
	v_lshl_add_u32 v2, v15, 13, v2
	v_and_b32_e32 v3, 1, v14
	s_add_i32 s20, s10, s5
	v_lshl_or_b32 v2, v3, 6, v2
	s_add_i32 s22, s7, 0
	s_add_i32 s20, s20, 0x20400
	v_mov_b32_e32 v137, v1
	v_lshl_add_u32 v138, v16, 1, v2
	v_mov_b32_e32 v139, v1
	s_mov_b32 s21, 0
	s_add_i32 s23, s22, 0x20500
	v_add_u32_e32 v154, 0, v18
	s_barrier
	s_branch .LBB0_123

.LBB0_719:
	v_readlane_b32 s10, v253, 47
	s_add_u32 s8, s4, 0x100080
	v_mov_b32_e32 v135, v1
	v_readlane_b32 s11, v253, 48
	s_addc_u32 s9, s5, 0
	s_add_i32 m0, s23, 0x18000
	v_lshl_add_u64 v[2:3], v[2:3], 0, s[88:89]
	v_lshl_add_u64 v[14:15], s[10:11], 0, v[134:135]
	v_mov_b32_e32 v137, v1
	global_load_lds_dwordx4 v[2:3], off
	v_lshl_add_u64 v[2:3], v[4:5], 0, s[88:89]
	s_add_i32 m0, s23, 0x1a000
	s_add_i32 s29, s23, 0x8000
	v_lshl_add_u64 v[16:17], s[10:11], 0, v[136:137]
	global_load_lds_dwordx4 v[2:3], off
	v_lshl_add_u64 v[2:3], v[14:15], 0, s[88:89]
	s_mov_b32 m0, s29
	s_add_i32 s30, s23, 0xa000
	global_load_lds_dwordx4 v[2:3], off
	v_lshl_add_u64 v[2:3], v[16:17], 0, s[88:89]
	s_mov_b32 m0, s30
	v_bfe_u32 v151, v10, 4, 2
	global_load_lds_dwordx4 v[2:3], off
	s_add_i32 m0, s23, 0x1c000
	v_lshl_add_u64 v[2:3], s[8:9], 0, v[0:1]
	global_load_lds_dwordx4 v[2:3], off
	v_lshl_add_u64 v[2:3], s[8:9], 0, v[138:139]
	s_add_i32 m0, s23, 0x1e000
	s_lshl_b32 s1, s1, 5
	global_load_lds_dwordx4 v[2:3], off
	s_cmp_lg_u32 s2, 1
	s_cbranch_scc1 .Lpro_skip1
	s_barrier
.Lpro_skip1:
	s_waitcnt vmcnt(8)
	s_barrier
	v_lshlrev_b32_e32 v2, 16, v6
	v_and_b32_e32 v2, 0xfffe0000, v2
	v_and_b32_e32 v150, 15, v10
	v_lshlrev_b32_e32 v13, 4, v151
	v_lshlrev_b32_e32 v10, 2, v10
	s_and_b32 s28, s1, 0x60
	v_lshl_add_u32 v2, v7, 13, v2
	v_and_b32_e32 v3, 1, v6
	s_lshl_b32 s27, s2, 6
	v_lshl_or_b32 v13, v150, 6, v13
	s_lshl_b32 s2, s2, 13
	v_and_b32_e32 v10, 32, v10
	s_lshl_b32 s1, s28, 7
	v_lshl_or_b32 v2, v3, 6, v2
	v_bitop3_b32 v152, v13, s1, v10 bitop3:0xde
	s_cmpk_lt_u32 s0, 0x100
	v_lshl_add_u32 v2, v8, 1, v2
	v_mov_b32_e32 v3, v1
	s_mov_b64 s[0:1], 0x100080
	v_lshl_add_u64 v[140:141], v[2:3], 0, s[0:1]
	v_lshlrev_b32_e32 v2, 16, v9
	v_and_b32_e32 v2, 0xfffe0000, v2
	v_lshl_add_u32 v2, v11, 13, v2
	v_and_b32_e32 v3, 1, v9
	v_lshl_or_b32 v2, v3, 6, v2
	s_waitcnt vmcnt(6)
	v_lshl_add_u32 v2, v12, 1, v2
	v_mov_b32_e32 v3, v1
	v_bitop3_b32 v18, v13, s2, v10 bitop3:0xde
	v_lshl_add_u64 v[142:143], v[2:3], 0, s[0:1]
	v_mov_b32_e32 v2, 0
	v_readlane_b32 s0, v253, 57
	s_cselect_b64 s[8:9], -1, 0
	s_mov_b32 s33, 0
	s_mov_b32 s31, 64
	s_mov_b32 s86, -1
	v_add_u32_e32 v153, 0, v18
	v_readlane_b32 s52, v253, 42
	s_mov_b32 s53, s0
	v_mov_b32_e32 v3, v2
	v_mov_b32_e32 v4, v2
	v_mov_b32_e32 v5, v2
	v_mov_b32_e32 v6, v2
	v_mov_b32_e32 v7, v2
	v_mov_b32_e32 v8, v2
	v_mov_b32_e32 v9, v2
	v_mov_b32_e32 v10, v2
	v_mov_b32_e32 v11, v2
	v_mov_b32_e32 v12, v2
	v_mov_b32_e32 v13, v2
	v_mov_b32_e32 v14, v2
	v_mov_b32_e32 v15, v2
	v_mov_b32_e32 v16, v2
	v_mov_b32_e32 v17, v2
	v_mov_b32_e32 v18, v2
	v_mov_b32_e32 v19, v2
	v_mov_b32_e32 v20, v2
	v_mov_b32_e32 v21, v2
	v_mov_b32_e32 v22, v2
	v_mov_b32_e32 v23, v2
	v_mov_b32_e32 v24, v2
	v_mov_b32_e32 v25, v2
	v_mov_b32_e32 v26, v2
	v_mov_b32_e32 v27, v2
	v_mov_b32_e32 v28, v2
	v_mov_b32_e32 v29, v2
	v_mov_b32_e32 v30, v2
	v_mov_b32_e32 v31, v2
	v_mov_b32_e32 v32, v2
	v_mov_b32_e32 v33, v2
	v_mov_b32_e32 v34, v2
	v_mov_b32_e32 v35, v2
	v_mov_b32_e32 v36, v2
	v_mov_b32_e32 v37, v2
	v_mov_b32_e32 v38, v2
	v_mov_b32_e32 v39, v2
	v_mov_b32_e32 v40, v2
	v_mov_b32_e32 v41, v2
	v_mov_b32_e32 v42, v2
	v_mov_b32_e32 v43, v2
	v_mov_b32_e32 v44, v2
	v_mov_b32_e32 v45, v2
	v_mov_b32_e32 v46, v2
	v_mov_b32_e32 v47, v2
	v_mov_b32_e32 v48, v2
	v_mov_b32_e32 v49, v2
	v_mov_b32_e32 v50, v2
	v_mov_b32_e32 v51, v2
	v_mov_b32_e32 v52, v2
	v_mov_b32_e32 v53, v2
	v_mov_b32_e32 v54, v2
	v_mov_b32_e32 v55, v2
	v_mov_b32_e32 v56, v2
	v_mov_b32_e32 v57, v2
	v_mov_b32_e32 v58, v2
	v_mov_b32_e32 v59, v2
	v_mov_b32_e32 v60, v2
	v_mov_b32_e32 v61, v2
	v_mov_b32_e32 v62, v2
	v_mov_b32_e32 v63, v2
	v_mov_b32_e32 v64, v2
	v_mov_b32_e32 v65, v2
	v_mov_b32_e32 v66, v2
	v_mov_b32_e32 v67, v2
	v_mov_b32_e32 v68, v2
	v_mov_b32_e32 v69, v2
	v_mov_b32_e32 v70, v2
	v_mov_b32_e32 v71, v2
	v_mov_b32_e32 v72, v2
	v_mov_b32_e32 v73, v2
	v_mov_b32_e32 v74, v2
	v_mov_b32_e32 v75, v2
	v_mov_b32_e32 v76, v2
	v_mov_b32_e32 v77, v2
	v_mov_b32_e32 v78, v2
	v_mov_b32_e32 v79, v2
	v_mov_b32_e32 v80, v2
	v_mov_b32_e32 v81, v2
	v_mov_b32_e32 v82, v2
	v_mov_b32_e32 v83, v2
	v_mov_b32_e32 v84, v2
	v_mov_b32_e32 v85, v2
	v_mov_b32_e32 v86, v2
	v_mov_b32_e32 v87, v2
	v_mov_b32_e32 v88, v2
	v_mov_b32_e32 v89, v2
	v_mov_b32_e32 v90, v2
	v_mov_b32_e32 v91, v2
	v_mov_b32_e32 v92, v2
	v_mov_b32_e32 v93, v2
	v_mov_b32_e32 v94, v2
	v_mov_b32_e32 v95, v2
	v_mov_b32_e32 v96, v2
	v_mov_b32_e32 v97, v2
	v_mov_b32_e32 v98, v2
	v_mov_b32_e32 v99, v2
	v_mov_b32_e32 v100, v2
	v_mov_b32_e32 v101, v2
	v_mov_b32_e32 v102, v2
	v_mov_b32_e32 v103, v2
	v_mov_b32_e32 v104, v2
	v_mov_b32_e32 v105, v2
	v_mov_b32_e32 v106, v2
	v_mov_b32_e32 v107, v2
	v_mov_b32_e32 v108, v2
	v_mov_b32_e32 v109, v2
	v_mov_b32_e32 v110, v2
	v_mov_b32_e32 v111, v2
	v_mov_b32_e32 v112, v2
	v_mov_b32_e32 v113, v2
	v_mov_b32_e32 v114, v2
	v_mov_b32_e32 v115, v2
	v_mov_b32_e32 v116, v2
	v_mov_b32_e32 v117, v2
	v_mov_b32_e32 v118, v2
	v_mov_b32_e32 v119, v2
	v_mov_b32_e32 v120, v2
	v_mov_b32_e32 v121, v2
	v_mov_b32_e32 v122, v2
	v_mov_b32_e32 v123, v2
	v_mov_b32_e32 v124, v2
	v_mov_b32_e32 v125, v2
	v_mov_b32_e32 v126, v2
	v_mov_b32_e32 v127, v2
	v_mov_b32_e32 v128, v2
	v_mov_b32_e32 v129, v2
	s_barrier
	v_readlane_b32 s1, v253, 58
	s_branch .LBB0_722

.LBB0_872:
	v_and_b32_e32 v218, 15, v0
	v_and_b32_e32 v219, 63, v0
	v_bfe_u32 v220, v0, 4, 2
	v_and_b32_e32 v20, 48, v0
	v_lshlrev_b32_e32 v0, 2, v0
	s_and_b32 s3, s7, 3
	s_lshl_b32 s24, s30, 13
	v_lshl_or_b32 v20, v218, 6, v20
	v_and_b32_e32 v0, 32, v0
	s_add_i32 m0, s9, 0x18000
	v_lshl_add_u64 v[8:9], v[8:9], 0, s[88:89]
	s_lshl_b32 s56, s30, 6
	v_bitop3_b32 v21, v20, s24, v0 bitop3:0xde
	s_lshl_b32 s57, s3, 5
	s_lshl_b32 s24, s3, 12
	global_load_lds_dwordx4 v[8:9], off
	v_lshl_add_u64 v[6:7], v[6:7], 0, s[88:89]
	s_add_i32 m0, s9, 0x1a000
	s_add_i32 s63, s9, 0x8000
	s_add_i32 s90, s9, 0xa000
	v_bitop3_b32 v221, v20, s24, v0 bitop3:0xde
	global_load_lds_dwordx4 v[6:7], off
	v_lshl_add_u64 v[2:3], v[2:3], 0, s[88:89]
	s_mov_b32 m0, s63
	s_add_u32 s24, s4, 0x100080
	global_load_lds_dwordx4 v[2:3], off
	v_lshl_add_u64 v[2:3], v[4:5], 0, s[88:89]
	s_mov_b32 m0, s90
	s_addc_u32 s25, s5, 0
	global_load_lds_dwordx4 v[2:3], off
	s_add_i32 m0, s9, 0x1c000
	v_lshl_add_u64 v[2:3], s[24:25], 0, v[182:183]
	global_load_lds_dwordx4 v[2:3], off
	v_lshl_add_u64 v[2:3], s[24:25], 0, v[186:187]
	s_add_i32 m0, s9, 0x1e000
	s_lshl_b32 s24, s7, 5
	global_load_lds_dwordx4 v[2:3], off
	s_cmp_lg_u32 s30, 1
	s_cbranch_scc1 .Lpro_skip2
	s_barrier
.Lpro_skip2:
	s_waitcnt vmcnt(8)
	s_barrier
	s_lshl_b32 s7, s7, 4
	s_and_b32 s91, s24, 0x60
	s_and_b32 s24, s7, 0xffffffc0
	s_ashr_i32 s25, s24, 31
	s_cmpk_lt_u32 s6, 0x100
	s_cselect_b64 s[94:95], -1, 0
	s_lshl_b32 s34, s30, 12
	s_lshl_b32 s3, s3, 10
	s_lshl_b64 s[6:7], s[24:25], 2
	v_readlane_b32 s24, v254, 7
	v_and_b32_e32 v2, 1, v10
	s_add_u32 s24, s24, s6
	v_readlane_b32 s6, v254, 8
	v_add3_u32 v0, v12, v13, v15
	v_lshlrev_b32_e32 v2, 6, v2
	s_addc_u32 s25, s6, s7
	s_add_i32 s6, s34, 0
	v_lshl_or_b32 v0, v0, 13, v2
	s_add_i32 s66, s6, s3
	v_lshl_add_u32 v0, v11, 1, v0
	s_mov_b64 s[6:7], 0x100080
	v_and_b32_e32 v2, 1, v14
	v_lshl_add_u64 v[188:189], v[0:1], 0, s[6:7]
	v_add3_u32 v0, v17, v18, v19
	v_lshlrev_b32_e32 v2, 6, v2
	s_waitcnt vmcnt(6)
	v_lshl_or_b32 v0, v0, 13, v2
	v_lshl_add_u32 v0, v16, 1, v0
	s_add_i32 s66, s66, 0x20400
	v_lshl_add_u64 v[190:191], v[0:1], 0, s[6:7]
	s_mov_b32 s67, 0
	v_add_u32_e32 v222, 0, v21
	s_barrier
	s_branch .LBB0_875

.LBB0_1154:
	v_readlane_b32 s10, v253, 59
	s_add_u32 s8, s4, 0x2b0080
	v_mov_b32_e32 v135, v1
	v_readlane_b32 s11, v253, 60
	s_addc_u32 s9, s5, 0
	s_add_i32 m0, s23, 0x18000
	v_lshl_add_u64 v[2:3], v[2:3], 0, s[88:89]
	v_lshl_add_u64 v[16:17], s[10:11], 0, v[134:135]
	v_mov_b32_e32 v137, v1
	global_load_lds_dwordx4 v[2:3], off
	v_lshl_add_u64 v[2:3], v[4:5], 0, s[88:89]
	s_add_i32 m0, s23, 0x1a000
	s_add_i32 s29, s23, 0x8000
	s_nop 0
	v_lshl_add_u64 v[18:19], s[10:11], 0, v[136:137]
	global_load_lds_dwordx4 v[2:3], off
	v_lshl_add_u64 v[2:3], v[16:17], 0, s[88:89]
	s_mov_b32 m0, s29
	s_add_i32 s30, s23, 0xa000
	global_load_lds_dwordx4 v[2:3], off
	v_lshl_add_u64 v[2:3], v[18:19], 0, s[88:89]
	s_mov_b32 m0, s30
	v_bfe_u32 v151, v11, 4, 2
	global_load_lds_dwordx4 v[2:3], off
	s_add_i32 m0, s23, 0x1c000
	v_lshl_add_u64 v[2:3], s[8:9], 0, v[0:1]
	global_load_lds_dwordx4 v[2:3], off
	v_lshl_add_u64 v[2:3], s[8:9], 0, v[138:139]
	s_add_i32 m0, s23, 0x1e000
	v_and_b32_e32 v150, 15, v11
	global_load_lds_dwordx4 v[2:3], off
	s_cmp_lg_u32 s0, 1
	s_cbranch_scc1 .Lpro_skip3
	s_barrier
.Lpro_skip3:
	s_waitcnt vmcnt(8)
	s_barrier
	v_lshlrev_b32_e32 v15, 4, v151
	v_lshlrev_b32_e32 v11, 2, v11
	s_lshl_b32 s27, s0, 6
	v_lshl_or_b32 v15, v150, 6, v15
	s_lshl_b32 s0, s0, 13
	v_and_b32_e32 v11, 32, v11
	v_bitop3_b32 v20, v15, s0, v11 bitop3:0xde
	s_lshl_b32 s0, s3, 5
	s_and_b32 s28, s0, 0x60
	s_lshl_b32 s0, s28, 7
	s_cmpk_lt_u32 s2, 0x100
	s_movk_i32 s2, 0x2b00
	v_lshrrev_b32_e32 v3, 1, v6
	v_mul_lo_u32 v2, v8, s2
	s_mov_b32 s3, 0x2b000
	v_bitop3_b32 v152, v15, s0, v11 bitop3:0xde
	v_mad_u64_u32 v[2:3], s[0:1], v3, s3, v[2:3]
	v_or_b32_e32 v2, v2, v7
	v_add_lshl_u32 v2, v2, v9, 1
	v_mov_b32_e32 v3, v1
	s_mov_b64 s[12:13], 0x2b0080
	v_lshl_add_u64 v[140:141], v[2:3], 0, s[12:13]
	v_lshrrev_b32_e32 v3, 1, v10
	v_mul_lo_u32 v2, v13, s2
	v_mad_u64_u32 v[2:3], s[0:1], v3, s3, v[2:3]
	v_or_b32_e32 v2, v2, v12
	s_waitcnt vmcnt(6)
	v_add_lshl_u32 v2, v2, v14, 1
	v_mov_b32_e32 v3, v1
	v_lshl_add_u64 v[142:143], v[2:3], 0, s[12:13]
	v_mov_b32_e32 v2, 0
	v_readlane_b32 s0, v253, 57
	s_cselect_b64 s[8:9], -1, 0
	s_mov_b32 s33, 0
	s_movk_i32 s31, 0xac
	s_mov_b32 s86, -1
	v_add_u32_e32 v153, 0, v20
	v_readlane_b32 s52, v253, 42
	s_mov_b32 s53, s0
	v_mov_b32_e32 v3, v2
	v_mov_b32_e32 v4, v2
	v_mov_b32_e32 v5, v2
	v_mov_b32_e32 v6, v2
	v_mov_b32_e32 v7, v2
	v_mov_b32_e32 v8, v2
	v_mov_b32_e32 v9, v2
	v_mov_b32_e32 v10, v2
	v_mov_b32_e32 v11, v2
	v_mov_b32_e32 v12, v2
	v_mov_b32_e32 v13, v2
	v_mov_b32_e32 v14, v2
	v_mov_b32_e32 v15, v2
	v_mov_b32_e32 v16, v2
	v_mov_b32_e32 v17, v2
	v_mov_b32_e32 v18, v2
	v_mov_b32_e32 v19, v2
	v_mov_b32_e32 v20, v2
	v_mov_b32_e32 v21, v2
	v_mov_b32_e32 v22, v2
	v_mov_b32_e32 v23, v2
	v_mov_b32_e32 v24, v2
	v_mov_b32_e32 v25, v2
	v_mov_b32_e32 v26, v2
	v_mov_b32_e32 v27, v2
	v_mov_b32_e32 v28, v2
	v_mov_b32_e32 v29, v2
	v_mov_b32_e32 v30, v2
	v_mov_b32_e32 v31, v2
	v_mov_b32_e32 v32, v2
	v_mov_b32_e32 v33, v2
	v_mov_b32_e32 v34, v2
	v_mov_b32_e32 v35, v2
	v_mov_b32_e32 v36, v2
	v_mov_b32_e32 v37, v2
	v_mov_b32_e32 v38, v2
	v_mov_b32_e32 v39, v2
	v_mov_b32_e32 v40, v2
	v_mov_b32_e32 v41, v2
	v_mov_b32_e32 v42, v2
	v_mov_b32_e32 v43, v2
	v_mov_b32_e32 v44, v2
	v_mov_b32_e32 v45, v2
	v_mov_b32_e32 v46, v2
	v_mov_b32_e32 v47, v2
	v_mov_b32_e32 v48, v2
	v_mov_b32_e32 v49, v2
	v_mov_b32_e32 v50, v2
	v_mov_b32_e32 v51, v2
	v_mov_b32_e32 v52, v2
	v_mov_b32_e32 v53, v2
	v_mov_b32_e32 v54, v2
	v_mov_b32_e32 v55, v2
	v_mov_b32_e32 v56, v2
	v_mov_b32_e32 v57, v2
	v_mov_b32_e32 v58, v2
	v_mov_b32_e32 v59, v2
	v_mov_b32_e32 v60, v2
	v_mov_b32_e32 v61, v2
	v_mov_b32_e32 v62, v2
	v_mov_b32_e32 v63, v2
	v_mov_b32_e32 v64, v2
	v_mov_b32_e32 v65, v2
	v_mov_b32_e32 v66, v2
	v_mov_b32_e32 v67, v2
	v_mov_b32_e32 v68, v2
	v_mov_b32_e32 v69, v2
	v_mov_b32_e32 v70, v2
	v_mov_b32_e32 v71, v2
	v_mov_b32_e32 v72, v2
	v_mov_b32_e32 v73, v2
	v_mov_b32_e32 v74, v2
	v_mov_b32_e32 v75, v2
	v_mov_b32_e32 v76, v2
	v_mov_b32_e32 v77, v2
	v_mov_b32_e32 v78, v2
	v_mov_b32_e32 v79, v2
	v_mov_b32_e32 v80, v2
	v_mov_b32_e32 v81, v2
	v_mov_b32_e32 v82, v2
	v_mov_b32_e32 v83, v2
	v_mov_b32_e32 v84, v2
	v_mov_b32_e32 v85, v2
	v_mov_b32_e32 v86, v2
	v_mov_b32_e32 v87, v2
	v_mov_b32_e32 v88, v2
	v_mov_b32_e32 v89, v2
	v_mov_b32_e32 v90, v2
	v_mov_b32_e32 v91, v2
	v_mov_b32_e32 v92, v2
	v_mov_b32_e32 v93, v2
	v_mov_b32_e32 v94, v2
	v_mov_b32_e32 v95, v2
	v_mov_b32_e32 v96, v2
	v_mov_b32_e32 v97, v2
	v_mov_b32_e32 v98, v2
	v_mov_b32_e32 v99, v2
	v_mov_b32_e32 v100, v2
	v_mov_b32_e32 v101, v2
	v_mov_b32_e32 v102, v2
	v_mov_b32_e32 v103, v2
	v_mov_b32_e32 v104, v2
	v_mov_b32_e32 v105, v2
	v_mov_b32_e32 v106, v2
	v_mov_b32_e32 v107, v2
	v_mov_b32_e32 v108, v2
	v_mov_b32_e32 v109, v2
	v_mov_b32_e32 v110, v2
	v_mov_b32_e32 v111, v2
	v_mov_b32_e32 v112, v2
	v_mov_b32_e32 v113, v2
	v_mov_b32_e32 v114, v2
	v_mov_b32_e32 v115, v2
	v_mov_b32_e32 v116, v2
	v_mov_b32_e32 v117, v2
	v_mov_b32_e32 v118, v2
	v_mov_b32_e32 v119, v2
	v_mov_b32_e32 v120, v2
	v_mov_b32_e32 v121, v2
	v_mov_b32_e32 v122, v2
	v_mov_b32_e32 v123, v2
	v_mov_b32_e32 v124, v2
	v_mov_b32_e32 v125, v2
	v_mov_b32_e32 v126, v2
	v_mov_b32_e32 v127, v2
	v_mov_b32_e32 v128, v2
	v_mov_b32_e32 v129, v2
	s_barrier
	v_readlane_b32 s1, v253, 58
	s_branch .LBB0_1157
